# split barrier before attention: units start without waiting for the GLA final phase; barrier completed at the first unit's output epilogue before its stores
# speedup vs baseline: 1.0012x; 1.0012x over previous
.Lpd_done_L0:
.LBB0_1243:
	s_mov_b32 s101, -1
	s_getreg_b32 s6, hwreg(HW_REG_XCC_ID, 0, 4)
	s_waitcnt vmcnt(0)
	s_barrier
	s_and_saveexec_b64 s[0:1], s[46:47]
	s_cbranch_execz .LBB0_1295
	s_add_i32 s7, 0, 0x20160
	v_mov_b32_e32 v0, s7
	s_waitcnt vmcnt(0) expcnt(0) lgkmcnt(0)
	ds_read_b32 v2, v0
	s_add_i32 s7, 0, 0x20164
	v_mov_b32_e32 v0, s7
	ds_read_b32 v0, v0
	s_and_b32 s51, s6, 15
	s_waitcnt lgkmcnt(1)
	v_cmp_ne_u32_e32 vcc, 0, v2
	s_cbranch_vccnz .LBB0_1259
	s_add_u32 s6, s66, 0x1200
	s_addc_u32 s7, s67, 0
	s_add_u32 s14, s66, 0x1400
	s_addc_u32 s15, s67, 0
	s_add_u32 s16, s66, 0x1500
	s_addc_u32 s17, s67, 0
	s_add_u32 s18, s66, 0x1600
	s_addc_u32 s19, s67, 0
	s_add_u32 s20, s66, 0x1700
	s_addc_u32 s21, s67, 0
	s_add_u32 s22, s66, 0x1800
	s_addc_u32 s23, s67, 0
	s_add_u32 s24, s66, 0x1900
	s_addc_u32 s25, s67, 0
	s_add_u32 s26, s66, 0x1a00
	s_addc_u32 s27, s67, 0
	s_add_u32 s28, s66, 0x1b00
	s_addc_u32 s29, s67, 0
	s_add_u32 s30, s66, 0x1c00
	s_addc_u32 s31, s67, 0
	s_add_u32 s34, s66, 0x1d00
	s_addc_u32 s35, s67, 0
	s_add_u32 s36, s66, 0x1e00
	s_addc_u32 s37, s67, 0
	s_add_u32 s38, s66, 0x1f00
	s_addc_u32 s39, s67, 0
	s_add_u32 s40, s66, 0x2000
	s_addc_u32 s41, s67, 0
	s_add_u32 s42, s66, 0x2100
	s_addc_u32 s43, s67, 0
	s_add_u32 s44, s66, 0x2200
	s_addc_u32 s45, s67, 0
	s_mul_i32 s72, s65, s74
	s_add_u32 s58, s66, 0x2300
	s_mul_i32 s72, s72, s64
	s_addc_u32 s59, s67, 0
	s_mov_b32 s73, 1
	v_mov_b32_e32 v16, 0
	s_branch .LBB0_1247

.LBB0_1261:
	s_or_b64 exec, exec, s[16:17]
	v_cvt_f32_u32_e32 v4, v2
	s_waitcnt vmcnt(0)
	v_readfirstlane_b32 s14, v3
	v_sub_u32_e32 v3, 0, v2
	v_rcp_iflag_f32_e32 v4, v4
	v_add_u32_e32 v5, s14, v1
	v_mul_f32_e32 v4, 0x4f7ffffe, v4
	v_cvt_u32_f32_e32 v4, v4
	v_mul_lo_u32 v1, v3, v4
	v_mul_hi_u32 v1, v4, v1
	v_add_u32_e32 v1, v4, v1
	v_mul_hi_u32 v1, v5, v1
	v_mul_lo_u32 v3, v1, v2
	v_sub_u32_e32 v3, v5, v3
	v_add_u32_e32 v4, 1, v1
	v_cmp_ge_u32_e32 vcc, v3, v2
	s_nop 1
	v_cndmask_b32_e32 v1, v1, v4, vcc
	v_sub_u32_e32 v4, v3, v2
	v_cndmask_b32_e32 v3, v3, v4, vcc
	v_add_u32_e32 v4, 1, v1
	v_cmp_ge_u32_e32 vcc, v3, v2
	v_add_u32_e32 v3, 1, v5
	s_nop 0
	v_cndmask_b32_e32 v1, v1, v4, vcc
	v_mul_lo_u32 v4, v2, v1
	v_add_u32_e32 v2, v4, v2
	v_cmp_ne_u32_e32 vcc, v3, v2
	s_and_saveexec_b64 s[14:15], vcc
	s_xor_b64 s[14:15], exec, s[14:15]
	s_cbranch_execz .LBB0_1275
	s_cmp_lt_u32 s2, 0
	s_cbranch_scc1 .Lsb_wait_r0
	s_cmp_lg_u32 s64, 0x100
	s_cbranch_scc1 .Lsb_wait_r0
	v_readfirstlane_b32 s101, v1
	s_branch .LBB0_1275

.LBB0_1298:
	s_or_b64 exec, exec, s[36:37]
	v_readfirstlane_b32 s98, v194
	s_cmp_lg_u32 s98, 0
	s_cbranch_scc1 .Lsb_cj_r0
	s_cmp_eq_u32 s101, -1
	s_cbranch_scc1 .Lsb_cj_r0
	s_getreg_b32 s98, hwreg(HW_REG_XCC_ID, 0, 4)
	s_lshl_b32 s98, s98, 8
	s_add_i32 s98, s98, 0x3400
	v_mov_b32_e32 v250, s98
	s_mov_b32 s99, 0

.Lsb_cj_r0:
	s_barrier
	s_waitcnt lgkmcnt(0)
	ds_read_b128 v[32:35], v188 offset:49280
	ds_read_b128 v[36:39], v188 offset:49312
	s_lshl_b64 s[6:7], s[34:35], 10
	s_add_u32 s6, s45, s6
	s_addc_u32 s7, s51, s7
	s_waitcnt lgkmcnt(1)
	v_rcp_f32_e32 v40, v32
	s_lshl_b32 s34, s79, 12
	v_rcp_f32_e32 v41, v33
	s_add_i32 s34, s34, 0
	v_lshlrev_b32_e32 v48, 9, v199
	v_lshlrev_b32_e32 v49, 1, v198
	v_mul_f32_e32 v0, v0, v40
	v_add3_u32 v48, s34, v48, v49
	v_cvt_pk_bf16_f32 v0, v0, s0
	v_rcp_f32_e32 v42, v34
	v_rcp_f32_e32 v43, v35
	s_waitcnt lgkmcnt(0)
	v_rcp_f32_e32 v44, v36
	ds_read_b128 v[32:35], v188 offset:49344
	v_rcp_f32_e32 v45, v37
	v_rcp_f32_e32 v46, v38
	v_rcp_f32_e32 v47, v39
	ds_read_b128 v[36:39], v188 offset:49376
	ds_write_b16 v48, v0 offset:51200
	v_mul_f32_e32 v0, v16, v40
	v_cvt_pk_bf16_f32 v0, v0, s0
	ds_write_b16 v48, v0 offset:51264
	v_mul_f32_e32 v0, v1, v41
	v_cvt_pk_bf16_f32 v0, v0, s0
	ds_write_b16 v48, v0 offset:51328
	v_mul_f32_e32 v0, v17, v41
	v_cvt_pk_bf16_f32 v0, v0, s0
	ds_write_b16 v48, v0 offset:51392
	v_mul_f32_e32 v0, v2, v42
	v_cvt_pk_bf16_f32 v0, v0, s0
	ds_write_b16 v48, v0 offset:51456
	v_mul_f32_e32 v0, v18, v42
	v_cvt_pk_bf16_f32 v0, v0, s0
	ds_write_b16 v48, v0 offset:51520
	v_mul_f32_e32 v0, v3, v43
	v_cvt_pk_bf16_f32 v0, v0, s0
	ds_write_b16 v48, v0 offset:51584
	v_mul_f32_e32 v0, v19, v43
	v_cvt_pk_bf16_f32 v0, v0, s0
	ds_write_b16 v48, v0 offset:51648
	v_mul_f32_e32 v0, v4, v44
	v_cvt_pk_bf16_f32 v0, v0, s0
	ds_write_b16 v48, v0 offset:52224
	v_mul_f32_e32 v0, v20, v44
	v_cvt_pk_bf16_f32 v0, v0, s0
	ds_write_b16 v48, v0 offset:52288
	v_mul_f32_e32 v0, v5, v45
	v_cvt_pk_bf16_f32 v0, v0, s0
	ds_write_b16 v48, v0 offset:52352
	v_mul_f32_e32 v0, v21, v45
	v_cvt_pk_bf16_f32 v0, v0, s0
	ds_write_b16 v48, v0 offset:52416
	v_mul_f32_e32 v0, v6, v46
	v_cvt_pk_bf16_f32 v0, v0, s0
	ds_write_b16 v48, v0 offset:52480
	v_mul_f32_e32 v0, v22, v46
	v_cvt_pk_bf16_f32 v0, v0, s0
	s_waitcnt lgkmcnt(14)
	v_rcp_f32_e32 v32, v32
	ds_write_b16 v48, v0 offset:52544
	v_mul_f32_e32 v0, v7, v47
	v_cvt_pk_bf16_f32 v0, v0, s0
	ds_write_b16 v48, v0 offset:52608
	v_mul_f32_e32 v0, v23, v47
	v_cvt_pk_bf16_f32 v0, v0, s0
	v_rcp_f32_e32 v33, v33
	ds_write_b16 v48, v0 offset:52672
	v_mul_f32_e32 v0, v8, v32
	v_cvt_pk_bf16_f32 v0, v0, s0
	ds_write_b16 v48, v0 offset:53248
	v_mul_f32_e32 v0, v24, v32
	v_cvt_pk_bf16_f32 v0, v0, s0
	v_rcp_f32_e32 v34, v34
	ds_write_b16 v48, v0 offset:53312
	v_mul_f32_e32 v0, v9, v33
	v_cvt_pk_bf16_f32 v0, v0, s0
	ds_write_b16 v48, v0 offset:53376
	v_mul_f32_e32 v0, v25, v33
	v_cvt_pk_bf16_f32 v0, v0, s0
	v_rcp_f32_e32 v35, v35
	ds_write_b16 v48, v0 offset:53440
	v_mul_f32_e32 v0, v10, v34
	v_cvt_pk_bf16_f32 v0, v0, s0
	ds_write_b16 v48, v0 offset:53504
	v_mul_f32_e32 v0, v26, v34
	v_cvt_pk_bf16_f32 v0, v0, s0
	s_waitcnt lgkmcnt(14)
	v_rcp_f32_e32 v36, v36
	ds_write_b16 v48, v0 offset:53568
	v_mul_f32_e32 v0, v11, v35
	v_cvt_pk_bf16_f32 v0, v0, s0
	ds_write_b16 v48, v0 offset:53632
	v_mul_f32_e32 v0, v27, v35
	v_cvt_pk_bf16_f32 v0, v0, s0
	v_rcp_f32_e32 v37, v37
	ds_write_b16 v48, v0 offset:53696
	v_mul_f32_e32 v0, v12, v36
	v_cvt_pk_bf16_f32 v0, v0, s0
	ds_write_b16 v48, v0 offset:54272
	v_mul_f32_e32 v0, v28, v36
	v_cvt_pk_bf16_f32 v0, v0, s0
	v_rcp_f32_e32 v38, v38
	ds_write_b16 v48, v0 offset:54336
	v_mul_f32_e32 v0, v13, v37
	v_cvt_pk_bf16_f32 v0, v0, s0
	ds_write_b16 v48, v0 offset:54400
	v_mul_f32_e32 v0, v29, v37
	v_cvt_pk_bf16_f32 v0, v0, s0
	v_rcp_f32_e32 v39, v39
	ds_write_b16 v48, v0 offset:54464
	v_mul_f32_e32 v0, v14, v38
	v_cvt_pk_bf16_f32 v0, v0, s0
	ds_write_b16 v48, v0 offset:54528
	v_mul_f32_e32 v0, v30, v38
	v_cvt_pk_bf16_f32 v0, v0, s0
	ds_write_b16 v48, v0 offset:54592
	v_mul_f32_e32 v0, v15, v39
	v_cvt_pk_bf16_f32 v0, v0, s0
	ds_write_b16 v48, v0 offset:54656
	v_mul_f32_e32 v0, v31, v39
	v_cvt_pk_bf16_f32 v0, v0, s0
	ds_write_b16 v48, v0 offset:54720
	v_lshlrev_b32_e32 v0, 1, v197
	v_and_b32_e32 v188, 0x70, v0
	v_lshrrev_b32_e32 v12, 3, v196
	v_add_u32_e32 v13, s34, v188
	s_waitcnt lgkmcnt(0)
	v_lshl_add_u32 v0, v12, 7, v13
	v_or_b32_e32 v14, 8, v12
	ds_read_b128 v[0:3], v0 offset:51200
	v_lshl_add_u32 v4, v14, 7, v13
	s_add_u32 s6, s6, s30
	ds_read_b128 v[4:7], v4 offset:51200
	s_addc_u32 s7, s7, s31
	v_lshl_add_u64 v[8:9], s[6:7], 0, v[188:189]
	v_lshlrev_b32_e32 v188, 10, v12
	v_lshl_add_u64 v[10:11], v[8:9], 0, v[188:189]
	v_lshlrev_b32_e32 v188, 10, v14
	s_waitcnt lgkmcnt(1)
	global_store_dwordx4 v[10:11], v[0:3], off
	s_add_i32 s43, s43, 1
	s_mov_b64 s[6:7], 0
	v_lshl_add_u64 v[0:1], v[8:9], 0, v[188:189]
	s_waitcnt lgkmcnt(0)
	global_store_dwordx4 v[0:1], v[4:7], off
	s_nop 1
	v_or_b32_e32 v4, 16, v12
	v_lshl_add_u32 v0, v4, 7, v13
	v_or_b32_e32 v12, 24, v12
	ds_read_b128 v[0:3], v0 offset:51200
	v_lshlrev_b32_e32 v188, 10, v4
	v_lshl_add_u32 v4, v12, 7, v13
	ds_read_b128 v[4:7], v4 offset:51200
	v_lshl_add_u64 v[10:11], v[8:9], 0, v[188:189]
	v_lshlrev_b32_e32 v188, 10, v12
	s_waitcnt lgkmcnt(1)
	global_store_dwordx4 v[10:11], v[0:3], off
	s_nop 1
	v_lshl_add_u64 v[0:1], v[8:9], 0, v[188:189]
	s_waitcnt lgkmcnt(0)
	global_store_dwordx4 v[0:1], v[4:7], off
	s_waitcnt lgkmcnt(0)
	s_barrier

.Lpd_done_L1:
.LBB0_2853:
	s_mov_b32 s101, -1
	s_getreg_b32 s8, hwreg(HW_REG_XCC_ID, 0, 4)
	s_waitcnt vmcnt(0)
	s_barrier
	s_and_saveexec_b64 s[0:1], s[46:47]
	s_cbranch_execz .LBB0_2905
	s_add_i32 s9, 0, 0x20160
	v_mov_b32_e32 v0, s9
	s_waitcnt vmcnt(0) expcnt(0) lgkmcnt(0)
	ds_read_b32 v2, v0
	s_add_i32 s9, 0, 0x20164
	v_mov_b32_e32 v0, s9
	ds_read_b32 v0, v0
	s_and_b32 s52, s8, 15
	s_waitcnt lgkmcnt(1)
	v_cmp_ne_u32_e32 vcc, 0, v2
	s_cbranch_vccnz .LBB0_2869
	s_add_u32 s8, s66, 0x1200
	s_addc_u32 s9, s67, 0
	s_add_u32 s10, s66, 0x1400
	s_addc_u32 s11, s67, 0
	s_add_u32 s12, s66, 0x1500
	s_addc_u32 s13, s67, 0
	s_add_u32 s14, s66, 0x1600
	s_addc_u32 s15, s67, 0
	s_add_u32 s16, s66, 0x1700
	s_addc_u32 s17, s67, 0
	s_add_u32 s18, s66, 0x1800
	s_addc_u32 s19, s67, 0
	s_add_u32 s20, s66, 0x1900
	s_addc_u32 s21, s67, 0
	s_add_u32 s22, s66, 0x1a00
	s_addc_u32 s23, s67, 0
	s_add_u32 s24, s66, 0x1b00
	s_addc_u32 s25, s67, 0
	s_add_u32 s26, s66, 0x1c00
	s_addc_u32 s27, s67, 0
	s_add_u32 s28, s66, 0x1d00
	s_addc_u32 s29, s67, 0
	s_add_u32 s30, s66, 0x1e00
	s_addc_u32 s31, s67, 0
	s_add_u32 s34, s66, 0x1f00
	s_addc_u32 s35, s67, 0
	s_add_u32 s36, s66, 0x2000
	s_addc_u32 s37, s67, 0
	s_add_u32 s38, s66, 0x2100
	s_addc_u32 s39, s67, 0
	s_add_u32 s40, s66, 0x2200
	s_addc_u32 s41, s67, 0
	s_mul_i32 s53, s65, s74
	s_add_u32 s42, s66, 0x2300
	s_mul_i32 s53, s53, s64
	s_addc_u32 s43, s67, 0
	s_mov_b32 s54, 1
	v_mov_b32_e32 v16, 0
	s_branch .LBB0_2857

.LBB0_2871:
	s_or_b64 exec, exec, s[12:13]
	v_cvt_f32_u32_e32 v4, v2
	s_waitcnt vmcnt(0)
	v_readfirstlane_b32 s10, v3
	v_sub_u32_e32 v3, 0, v2
	v_rcp_iflag_f32_e32 v4, v4
	v_add_u32_e32 v5, s10, v1
	v_mul_f32_e32 v4, 0x4f7ffffe, v4
	v_cvt_u32_f32_e32 v4, v4
	v_mul_lo_u32 v1, v3, v4
	v_mul_hi_u32 v1, v4, v1
	v_add_u32_e32 v1, v4, v1
	v_mul_hi_u32 v1, v5, v1
	v_mul_lo_u32 v3, v1, v2
	v_sub_u32_e32 v3, v5, v3
	v_add_u32_e32 v4, 1, v1
	v_cmp_ge_u32_e32 vcc, v3, v2
	s_nop 1
	v_cndmask_b32_e32 v1, v1, v4, vcc
	v_sub_u32_e32 v4, v3, v2
	v_cndmask_b32_e32 v3, v3, v4, vcc
	v_add_u32_e32 v4, 1, v1
	v_cmp_ge_u32_e32 vcc, v3, v2
	v_add_u32_e32 v3, 1, v5
	s_nop 0
	v_cndmask_b32_e32 v1, v1, v4, vcc
	v_mul_lo_u32 v4, v2, v1
	v_add_u32_e32 v2, v4, v2
	v_cmp_ne_u32_e32 vcc, v3, v2
	s_and_saveexec_b64 s[10:11], vcc
	s_xor_b64 s[10:11], exec, s[10:11]
	s_cbranch_execz .LBB0_2885
	s_cmp_lt_u32 s2, 0
	s_cbranch_scc1 .Lsb_wait_r1
	s_cmp_lg_u32 s64, 0x100
	s_cbranch_scc1 .Lsb_wait_r1
	v_readfirstlane_b32 s101, v1
	s_branch .LBB0_2885
.Lsb_wait_r1:
	s_waitcnt lgkmcnt(0)
	buffer_inv sc1
	v_mov_b32_e32 v0, 0x2000
	global_load_dword v0, v0, s[8:9] offset:1024 sc1
	s_add_u32 s16, s8, 0x2400
	s_addc_u32 s17, s9, 0
	s_waitcnt vmcnt(0)
	v_cmp_eq_u32_e32 vcc, v0, v1
	s_and_saveexec_b64 s[12:13], vcc
	s_cbranch_execz .LBB0_2884
	s_add_u32 s14, s66, 0x1200
	s_addc_u32 s15, s67, 0
	s_mov_b32 s28, 1
	s_mov_b64 s[18:19], 0
	v_mov_b32_e32 v0, 0
	s_branch .LBB0_2875

.LBB0_2908:
	s_or_b64 exec, exec, s[30:31]
	v_readfirstlane_b32 s98, v194
	s_cmp_lg_u32 s98, 0
	s_cbranch_scc1 .Lsb_cj_r1
	s_cmp_eq_u32 s101, -1
	s_cbranch_scc1 .Lsb_cj_r1
	s_getreg_b32 s98, hwreg(HW_REG_XCC_ID, 0, 4)
	s_lshl_b32 s98, s98, 8
	s_add_i32 s98, s98, 0x3400
	v_mov_b32_e32 v250, s98
	s_mov_b32 s99, 0

.Lsb_cj_r1:
	s_barrier
	s_waitcnt lgkmcnt(0)
	ds_read_b128 v[32:35], v188 offset:49280
	ds_read_b128 v[36:39], v188 offset:49312
	s_lshl_b64 s[8:9], s[28:29], 10
	s_add_u32 s8, s41, s8
	s_addc_u32 s9, s42, s9
	s_waitcnt lgkmcnt(1)
	v_rcp_f32_e32 v40, v32
	s_lshl_b32 s28, s56, 12
	v_rcp_f32_e32 v41, v33
	s_add_i32 s28, s28, 0
	v_lshlrev_b32_e32 v48, 9, v199
	v_lshlrev_b32_e32 v49, 1, v198
	v_mul_f32_e32 v0, v0, v40
	v_add3_u32 v48, s28, v48, v49
	v_cvt_pk_bf16_f32 v0, v0, s0
	v_rcp_f32_e32 v42, v34
	v_rcp_f32_e32 v43, v35
	s_waitcnt lgkmcnt(0)
	v_rcp_f32_e32 v44, v36
	ds_read_b128 v[32:35], v188 offset:49344
	v_rcp_f32_e32 v45, v37
	v_rcp_f32_e32 v46, v38
	v_rcp_f32_e32 v47, v39
	ds_read_b128 v[36:39], v188 offset:49376
	ds_write_b16 v48, v0 offset:51200
	v_mul_f32_e32 v0, v16, v40
	v_cvt_pk_bf16_f32 v0, v0, s0
	ds_write_b16 v48, v0 offset:51264
	v_mul_f32_e32 v0, v1, v41
	v_cvt_pk_bf16_f32 v0, v0, s0
	ds_write_b16 v48, v0 offset:51328
	v_mul_f32_e32 v0, v17, v41
	v_cvt_pk_bf16_f32 v0, v0, s0
	ds_write_b16 v48, v0 offset:51392
	v_mul_f32_e32 v0, v2, v42
	v_cvt_pk_bf16_f32 v0, v0, s0
	ds_write_b16 v48, v0 offset:51456
	v_mul_f32_e32 v0, v18, v42
	v_cvt_pk_bf16_f32 v0, v0, s0
	ds_write_b16 v48, v0 offset:51520
	v_mul_f32_e32 v0, v3, v43
	v_cvt_pk_bf16_f32 v0, v0, s0
	ds_write_b16 v48, v0 offset:51584
	v_mul_f32_e32 v0, v19, v43
	v_cvt_pk_bf16_f32 v0, v0, s0
	ds_write_b16 v48, v0 offset:51648
	v_mul_f32_e32 v0, v4, v44
	v_cvt_pk_bf16_f32 v0, v0, s0
	ds_write_b16 v48, v0 offset:52224
	v_mul_f32_e32 v0, v20, v44
	v_cvt_pk_bf16_f32 v0, v0, s0
	ds_write_b16 v48, v0 offset:52288
	v_mul_f32_e32 v0, v5, v45
	v_cvt_pk_bf16_f32 v0, v0, s0
	ds_write_b16 v48, v0 offset:52352
	v_mul_f32_e32 v0, v21, v45
	v_cvt_pk_bf16_f32 v0, v0, s0
	ds_write_b16 v48, v0 offset:52416
	v_mul_f32_e32 v0, v6, v46
	v_cvt_pk_bf16_f32 v0, v0, s0
	ds_write_b16 v48, v0 offset:52480
	v_mul_f32_e32 v0, v22, v46
	v_cvt_pk_bf16_f32 v0, v0, s0
	s_waitcnt lgkmcnt(14)
	v_rcp_f32_e32 v32, v32
	ds_write_b16 v48, v0 offset:52544
	v_mul_f32_e32 v0, v7, v47
	v_cvt_pk_bf16_f32 v0, v0, s0
	ds_write_b16 v48, v0 offset:52608
	v_mul_f32_e32 v0, v23, v47
	v_cvt_pk_bf16_f32 v0, v0, s0
	v_rcp_f32_e32 v33, v33
	ds_write_b16 v48, v0 offset:52672
	v_mul_f32_e32 v0, v8, v32
	v_cvt_pk_bf16_f32 v0, v0, s0
	ds_write_b16 v48, v0 offset:53248
	v_mul_f32_e32 v0, v24, v32
	v_cvt_pk_bf16_f32 v0, v0, s0
	v_rcp_f32_e32 v34, v34
	ds_write_b16 v48, v0 offset:53312
	v_mul_f32_e32 v0, v9, v33
	v_cvt_pk_bf16_f32 v0, v0, s0
	ds_write_b16 v48, v0 offset:53376
	v_mul_f32_e32 v0, v25, v33
	v_cvt_pk_bf16_f32 v0, v0, s0
	v_rcp_f32_e32 v35, v35
	ds_write_b16 v48, v0 offset:53440
	v_mul_f32_e32 v0, v10, v34
	v_cvt_pk_bf16_f32 v0, v0, s0
	ds_write_b16 v48, v0 offset:53504
	v_mul_f32_e32 v0, v26, v34
	v_cvt_pk_bf16_f32 v0, v0, s0
	s_waitcnt lgkmcnt(14)
	v_rcp_f32_e32 v36, v36
	ds_write_b16 v48, v0 offset:53568
	v_mul_f32_e32 v0, v11, v35
	v_cvt_pk_bf16_f32 v0, v0, s0
	ds_write_b16 v48, v0 offset:53632
	v_mul_f32_e32 v0, v27, v35
	v_cvt_pk_bf16_f32 v0, v0, s0
	v_rcp_f32_e32 v37, v37
	ds_write_b16 v48, v0 offset:53696
	v_mul_f32_e32 v0, v12, v36
	v_cvt_pk_bf16_f32 v0, v0, s0
	ds_write_b16 v48, v0 offset:54272
	v_mul_f32_e32 v0, v28, v36
	v_cvt_pk_bf16_f32 v0, v0, s0
	v_rcp_f32_e32 v38, v38
	ds_write_b16 v48, v0 offset:54336
	v_mul_f32_e32 v0, v13, v37
	v_cvt_pk_bf16_f32 v0, v0, s0
	ds_write_b16 v48, v0 offset:54400
	v_mul_f32_e32 v0, v29, v37
	v_cvt_pk_bf16_f32 v0, v0, s0
	v_rcp_f32_e32 v39, v39
	ds_write_b16 v48, v0 offset:54464
	v_mul_f32_e32 v0, v14, v38
	v_cvt_pk_bf16_f32 v0, v0, s0
	ds_write_b16 v48, v0 offset:54528
	v_mul_f32_e32 v0, v30, v38
	v_cvt_pk_bf16_f32 v0, v0, s0
	ds_write_b16 v48, v0 offset:54592
	v_mul_f32_e32 v0, v15, v39
	v_cvt_pk_bf16_f32 v0, v0, s0
	ds_write_b16 v48, v0 offset:54656
	v_mul_f32_e32 v0, v31, v39
	v_cvt_pk_bf16_f32 v0, v0, s0
	ds_write_b16 v48, v0 offset:54720
	v_lshlrev_b32_e32 v0, 1, v197
	v_and_b32_e32 v188, 0x70, v0
	v_lshrrev_b32_e32 v12, 3, v196
	v_add_u32_e32 v13, s28, v188
	s_waitcnt lgkmcnt(0)
	v_lshl_add_u32 v0, v12, 7, v13
	v_or_b32_e32 v14, 8, v12
	ds_read_b128 v[0:3], v0 offset:51200
	v_lshl_add_u32 v4, v14, 7, v13
	s_add_u32 s8, s8, s26
	ds_read_b128 v[4:7], v4 offset:51200
	s_addc_u32 s9, s9, s27
	v_lshl_add_u64 v[8:9], s[8:9], 0, v[188:189]
	v_lshlrev_b32_e32 v188, 10, v12
	v_lshl_add_u64 v[10:11], v[8:9], 0, v[188:189]
	v_lshlrev_b32_e32 v188, 10, v14
	s_waitcnt lgkmcnt(1)
	global_store_dwordx4 v[10:11], v[0:3], off
	s_add_i32 s39, s39, 1
	s_mov_b64 s[8:9], 0
	v_lshl_add_u64 v[0:1], v[8:9], 0, v[188:189]
	s_waitcnt lgkmcnt(0)
	global_store_dwordx4 v[0:1], v[4:7], off
	s_nop 1
	v_or_b32_e32 v4, 16, v12
	v_lshl_add_u32 v0, v4, 7, v13
	v_or_b32_e32 v12, 24, v12
	ds_read_b128 v[0:3], v0 offset:51200
	v_lshlrev_b32_e32 v188, 10, v4
	v_lshl_add_u32 v4, v12, 7, v13
	ds_read_b128 v[4:7], v4 offset:51200
	v_lshl_add_u64 v[10:11], v[8:9], 0, v[188:189]
	v_lshlrev_b32_e32 v188, 10, v12
	s_waitcnt lgkmcnt(1)
	global_store_dwordx4 v[10:11], v[0:3], off
	s_nop 1
	v_lshl_add_u64 v[0:1], v[8:9], 0, v[188:189]
	s_waitcnt lgkmcnt(0)
	global_store_dwordx4 v[0:1], v[4:7], off
	s_waitcnt lgkmcnt(0)
	s_barrier
